# attention prefetch also carries the per-head sink value (no in-iteration sink load)
# baseline (speedup 1.0000x reference)
; #define LAS __attribute__((address_space(3)))
; __device__ __forceinline__ void attn_phase(LAS unsigned char* lds, int vcu, int G, const bf16* Qp, const bf16* Kp, const bf16* Vt, const float* sinks, bf16* AO, int ldo, float* st) {
;     ...
;     const int lane = tid & 63, wave = __builtin_amdgcn_readfirstlane(tid >> 6), r32 = lane & 31, hi = lane >> 5, hq = wave & 3, qsub = wave >> 2;
;     const float NEG = -INFINITY;
;     float ssq_acc = 0.f;
;     for (int it = 0; it < 4; ++it) { const int id = ((vcu >> 5) << 7) | (it << 5) | (vcu & 31);
;         const int b = id >> 7, kvh = (id >> 5) & 3, q0 = 64 * (id & 31), h = kvh * 4 + hq;
;         const size_t tok0 = (size_t)b * SEQ;
;         const int jt0 = (q0 >= 128) ? 0 : (128 - q0) / 32;
;         v4u kv[3], vv[3];
; #pragma unroll
;         for (int i = 0; i < 3; ++i) { const int c = tid + 512 * i, row = c >> 3, ch = c & 7, key = q0 - 128 + row;
;             if (key >= 0) kv[i] = *(const v4u*)(Kp + (tok0 + key) * D_KV + kvh * HD + ch * 8); }
; #pragma unroll
;         for (int i = 0; i < 3; ++i) { const int c = tid + 512 * i, d = c / 24, ch = c - d * 24, key0 = q0 - 128 + 8 * ch;
;             if (key0 >= 0) vv[i] = *(const v4u*)(Vt + (size_t)(kvh * HD + d) * M + tok0 + key0); }
;         const bf16* qrow = Qp + (tok0 + q0 + 32 * qsub + r32) * D_ATTN + h * HD + 32 * hi;
;         bf16x8 qf[4];
; #pragma unroll
;         for (int kk = 0; kk < 4; ++kk) qf[kk] = *(const bf16x8*)(qrow + 8 * kk);
; #pragma unroll
;         for (int i = 0; i < 3; ++i) { const int c = tid + 512 * i, row = c >> 3, ch = c & 7, key = q0 - 128 + row;
;             if (key >= 0) *(LAS v4u*)(lds + row * AT_KROW + ch * 16) = kv[i]; }
; #pragma unroll
;         for (int i = 0; i < 3; ++i) { const int c = tid + 512 * i, d = c / 24, ch = c - d * 24, key0 = q0 - 128 + 8 * ch;
;             if (key0 >= 0) { LAS u64* p = (LAS u64*)(lds + AT_V_OFF + d * AT_VROW + ch * 16); p[0] = ((u64)vv[i].y << 32) | vv[i].x; p[1] = ((u64)vv[i].w << 32) | vv[i].z; } }
;         LDS_WAIT(); __syncthreads();
;         f32x16 s[5];
; #pragma unroll
;         for (int kt = 0; kt < 5; ++kt) {
;             if (kt + qsub >= jt0) {
;                 const LAS unsigned char* kp = lds + (32 * (kt + qsub) + r32) * AT_KROW + 64 * hi;
;                 f32x16 acc = {0.f, 0.f, 0.f, 0.f, 0.f, 0.f, 0.f, 0.f, 0.f, 0.f, 0.f, 0.f, 0.f, 0.f, 0.f, 0.f};
; #pragma unroll
.LBB0_654:
	v_writelane_b32 v254, s88, 53
	v_mov_b32_e32 v4, v0
	s_mov_b32 s15, 0x2aaaaaab
	v_writelane_b32 v254, s89, 54
	v_writelane_b32 v254, s2, 55
	v_readfirstlane_b32 s68, v4
	s_lshr_b32 s0, s68, 6
	v_writelane_b32 v254, s3, 56
	v_writelane_b32 v254, s0, 57
	s_lshl_b32 s0, s90, 6
	v_mul_hi_i32 v9, v4, s15
	s_bfe_i32 s66, s90, 0x190005
	s_and_b32 s3, s0, 0x7c0
	v_add_u32_e32 v8, 0x200, v4
	v_lshrrev_b32_e32 v13, 31, v9
	v_ashrrev_i32_e32 v9, 2, v9
	s_ashr_i32 s67, s66, 31
	v_mov_b32_e32 v3, s3
	s_sub_i32 s0, 0x80, s3
	v_add_u32_e32 v16, v9, v13
	v_mul_hi_i32 v9, v8, s15
	s_ashr_i32 s2, s68, 8
	s_lshl_b64 s[62:63], s[66:67], 11
	v_sub_co_u32_e32 v3, vcc, 0x7f, v3
	s_lshr_b32 s4, s0, 5
	v_lshrrev_b32_e32 v13, 31, v9
	v_ashrrev_i32_e32 v9, 2, v9
	s_and_b64 s[0:1], vcc, exec
	s_movk_i32 s16, 0xffe8
	v_add_u32_e32 v22, v9, v13
	s_cselect_b32 s28, 0, s4
	v_ashrrev_i32_e32 v25, 3, v8
	v_mad_u64_u32 v[8:9], s[4:5], v22, s16, v[8:9]
	s_add_i32 s14, s3, 0xffffff80
	v_lshlrev_b32_e32 v9, 3, v8
	v_add_u32_e32 v12, 0x400, v4
	v_add_u32_e32 v13, s14, v9
	v_cmp_lt_i32_e64 s[12:13], -1, v13
	v_mul_hi_i32 v13, v12, s15
	v_bfe_u32 v141, v4, 5, 1
	v_lshlrev_b32_e32 v5, 4, v4
	v_lshrrev_b32_e32 v24, 31, v13
	v_ashrrev_i32_e32 v13, 2, v13
	s_lshl_b32 s76, s2, 5
	v_and_b32_e32 v26, 0x70, v5
	v_lshlrev_b32_e32 v5, 2, v141
	v_add_u32_e32 v24, v13, v24
	s_ashr_i32 s77, s76, 31
	v_ashrrev_i32_e32 v30, 3, v12
	v_mad_u64_u32 v[18:19], s[4:5], v16, s16, v[4:5]
	v_mad_u64_u32 v[12:13], s[4:5], v24, s16, v[12:13]
	v_ashrrev_i32_e32 v23, 3, v4
	v_lshlrev_b32_e32 v19, 3, v18
	v_lshlrev_b32_e32 v13, 3, v12
	s_movk_i32 s5, 0x188
	s_cmp_ge_i32 s2, s28
	v_add_u32_e32 v20, s14, v19
	v_cmp_gt_i32_e64 s[16:17], v23, v3
	v_cmp_gt_i32_e64 s[18:19], v25, v3
	v_cmp_gt_i32_e64 s[20:21], v30, v3
	v_cmp_gt_i32_e64 s[22:23], v19, v3
	v_mul_lo_u32 v19, v16, s5
	v_cmp_gt_i32_e64 s[24:25], v9, v3
	v_mul_lo_u32 v9, v22, s5
	v_cmp_gt_i32_e64 s[26:27], v13, v3
	v_mul_lo_u32 v3, v24, s5
	s_cselect_b64 s[82:83], -1, 0
	s_add_i32 s5, s2, 1
	s_cmp_ge_i32 s5, s28
	v_and_b32_e32 v140, 31, v4
	s_cselect_b64 s[72:73], -1, 0
	s_add_i32 s60, s2, 2
	s_movk_i32 s4, 0x90
	v_lshlrev_b32_e32 v34, 4, v8
	v_or_b32_e32 v8, s76, v140
	s_cmp_ge_i32 s60, s28
	v_mul_lo_u32 v36, v8, s4
	v_lshl_or_b32 v8, s5, 5, v140
	s_cselect_b64 s[88:89], -1, 0
	s_add_i32 s69, s2, 3
	v_mul_lo_u32 v37, v8, s4
	v_lshl_or_b32 v8, s60, 5, v140
	s_cmp_ge_i32 s69, s28
	v_mul_lo_u32 v38, v8, s4
	s_cselect_b64 s[96:97], -1, 0
	v_lshl_or_b32 v8, s69, 5, v140
	s_add_i32 s70, s2, 4
	v_mul_lo_u32 v39, v8, s4
	v_lshl_or_b32 v8, s70, 5, v140
	v_mul_lo_u32 v40, v8, s4
	v_or_b32_e32 v8, 2, v5
	v_cmp_gt_u32_e64 s[34:35], v8, v140
	v_or_b32_e32 v8, 3, v5
	v_cmp_gt_u32_e64 s[36:37], v8, v140
	v_or_b32_e32 v8, 8, v5
	v_cmp_gt_u32_e64 s[38:39], v8, v140
	v_or_b32_e32 v8, 9, v5
	v_cmp_gt_u32_e64 s[40:41], v8, v140
	v_or_b32_e32 v8, 10, v5
	v_cmp_gt_u32_e64 s[42:43], v8, v140
	v_or_b32_e32 v8, 11, v5
	v_cmp_gt_u32_e64 s[44:45], v8, v140
	v_or_b32_e32 v8, 16, v5
	v_cmp_gt_u32_e64 s[46:47], v8, v140
	v_or_b32_e32 v8, 17, v5
	v_cmp_gt_u32_e64 s[48:49], v8, v140
	v_or_b32_e32 v8, 18, v5
	v_lshlrev_b32_e32 v28, 6, v141
	v_cmp_gt_u32_e64 s[50:51], v8, v140
	v_or_b32_e32 v8, 19, v5
	v_add_u32_e32 v29, 0, v28
	s_movk_i32 s0, 0xffc8
	v_cmp_gt_u32_e64 s[52:53], v8, v140
	v_or_b32_e32 v8, 24, v5
	v_mad_i32_i24 v17, v141, s0, v29
	v_add_u32_e32 v31, s14, v13
	v_cmp_gt_u32_e64 s[54:55], v8, v140
	v_or_b32_e32 v8, 25, v5
	v_add_u32_e32 v6, s14, v23
	v_add_u32_e32 v10, s14, v25
	v_add_u32_e32 v14, s14, v30
	v_cmp_lt_i32_e64 s[14:15], -1, v31
	v_mul_lo_u32 v31, v23, s4
	v_mul_lo_u32 v32, v25, s4
	s_cmp_ge_i32 s70, s28
	v_cmp_gt_u32_e64 s[56:57], v8, v140
	v_or_b32_e32 v8, 26, v5
	v_lshl_add_u32 v41, s5, 6, v17
	v_lshl_add_u32 v42, s60, 6, v17
	v_lshl_add_u32 v43, s2, 6, v17
	v_lshl_add_u32 v45, s69, 6, v17
	v_lshl_add_u32 v46, s70, 6, v17
	v_ashrrev_i32_e32 v17, 31, v16
	v_ashrrev_i32_e32 v23, 31, v22
	v_ashrrev_i32_e32 v25, 31, v24
	v_mul_lo_u32 v30, v30, s4
	v_add_u32_e32 v33, 0, v9
	v_lshlrev_b32_e32 v35, 4, v12
	s_cselect_b64 s[74:75], -1, 0
	v_cmp_gt_u32_e64 s[58:59], v8, v140
	v_lshlrev_b64 v[8:9], 15, v[16:17]
	s_lshl_b64 s[4:5], s[66:67], 12
	v_lshlrev_b64 v[12:13], 15, v[22:23]
	v_lshlrev_b64 v[16:17], 15, v[24:25]
; __device__ __forceinline__ void attn_phase(LAS unsigned char* lds, int vcu, int G, const bf16* Qp, const bf16* Kp, const bf16* Vt, const float* sinks, bf16* AO, int ldo, float* st) {
;     ...
;     for (int it = 0; it < 4; ++it) { const int id = ((vcu >> 5) << 7) | (it << 5) | (vcu & 31);
;         const int b = id >> 7, kvh = (id >> 5) & 3, q0 = 64 * (id & 31), h = kvh * 4 + hq;
;         const size_t tok0 = (size_t)b * SEQ;
;         const int jt0 = (q0 >= 128) ? 0 : (128 - q0) / 32;
;         v4u kv[3], vv[3];
; #pragma unroll
;         for (int i = 0; i < 3; ++i) { const int c = tid + 512 * i, row = c >> 3, ch = c & 7, key = q0 - 128 + row;
;             if (key >= 0) kv[i] = *(const v4u*)(Kp + (tok0 + key) * D_KV + kvh * HD + ch * 8); }
; #pragma unroll
;         for (int i = 0; i < 3; ++i) { const int c = tid + 512 * i, d = c / 24, ch = c - d * 24, key0 = q0 - 128 + 8 * ch;
;             if (key0 >= 0) vv[i] = *(const v4u*)(Vt + (size_t)(kvh * HD + d) * M + tok0 + key0); }
;         const bf16* qrow = Qp + (tok0 + q0 + 32 * qsub + r32) * D_ATTN + h * HD + 32 * hi;
;         bf16x8 qf[4];
; #pragma unroll
;         for (int kk = 0; kk < 4; ++kk) qf[kk] = *(const bf16x8*)(qrow + 8 * kk);
;     ...
;         const float sk = sinks[h] * 1.4426950408889634f;
	v_mov_b32_e32 v21, v2
	v_cmp_gt_u32_e64 s[28:29], v5, v140
	v_cmp_lt_u32_e64 s[30:31], v5, v140
	v_or_b32_e32 v5, 27, v5
	v_lshl_add_u64 v[8:9], v[8:9], 0, s[4:5]
	v_lshl_add_u64 v[12:13], v[12:13], 0, s[4:5]
	v_lshl_add_u64 v[16:17], v[16:17], 0, s[4:5]
	s_movk_i32 s4, 0xc0
	v_cmp_lt_i32_e64 s[10:11], -1, v20
	v_cmp_gt_u32_e64 s[60:61], v5, v140
	v_lshl_add_u64 v[8:9], v[20:21], 1, v[8:9]
	v_mul_lo_u32 v5, v22, s4
	v_mul_lo_u32 v20, v24, s4
	s_mov_b64 s[4:5], 0xd800000
	v_lshl_add_u64 v[124:125], v[8:9], 0, s[4:5]
	v_lshl_add_u32 v8, v4, 3, s3
	v_sub_u32_e32 v4, v8, v5
	v_add_u32_e32 v4, 0xf80, v4
	v_mov_b32_e32 v5, v2
	v_lshl_add_u64 v[4:5], v[4:5], 1, v[12:13]
	v_lshl_add_u64 v[126:127], v[4:5], 0, s[4:5]
	v_sub_u32_e32 v4, v8, v20
	v_add_u32_e32 v4, 0x1f80, v4
	v_mov_b32_e32 v5, v2
	v_mov_b32_e32 v7, v2
	v_lshl_add_u64 v[4:5], v[4:5], 1, v[16:17]
	v_lshl_add_u64 v[128:129], v[4:5], 0, s[4:5]
	s_lshl_b64 s[4:5], s[66:67], 20
	v_lshlrev_b64 v[4:5], 9, v[6:7]
	v_lshl_add_u64 v[4:5], s[4:5], 0, v[4:5]
	v_mov_b32_e32 v11, v2
	v_or_b32_e32 v4, v4, v26
	s_mov_b64 s[66:67], 0xd000000
	v_lshl_add_u64 v[130:131], v[4:5], 0, s[66:67]
	v_lshlrev_b64 v[4:5], 9, v[10:11]
	v_lshl_add_u64 v[4:5], s[4:5], 0, v[4:5]
	v_mov_b32_e32 v15, v2
	v_or_b32_e32 v4, v4, v26
	v_lshl_add_u64 v[132:133], v[4:5], 0, s[66:67]
	v_lshlrev_b64 v[4:5], 9, v[14:15]
	v_lshl_add_u64 v[4:5], s[4:5], 0, v[4:5]
	s_lshr_b32 s4, s68, 4
	s_and_b32 s4, s4, 12
	s_add_u32 s4, s64, s4
	s_addc_u32 s5, s65, 0
	v_writelane_b32 v254, s90, 58
	v_or_b32_e32 v4, v4, v26
	s_add_u32 s62, s62, s76
	v_lshl_add_u64 v[134:135], v[4:5], 0, s[66:67]
	v_writelane_b32 v254, s76, 59
	s_addc_u32 s63, s63, s77
	v_or_b32_e32 v4, s3, v140
	v_mov_b32_e32 v5, v2
	v_lshl_add_u64 v[4:5], s[62:63], 0, v[4:5]
	s_lshl_b32 s62, s68, 1
	v_cmp_lt_i32_e64 s[0:1], -1, v6
	v_lshlrev_b64 v[6:7], 12, v[4:5]
	s_and_b32 s64, s62, 0x180
	v_lshlrev_b32_e32 v8, 3, v141
	v_or3_b32 v6, v6, s64, v8
	s_mov_b64 s[62:63], 0xf000040
	v_lshlrev_b64 v[4:5], 11, v[4:5]
	v_lshl_add_u64 v[136:137], v[6:7], 0, s[62:63]
	v_or3_b32 v4, v4, s64, v28
	s_mov_b64 s[62:63], 0xb000020
	v_add_u32_e32 v27, 0, v26
	v_add_u32_e32 v19, 0, v19
	v_lshlrev_b32_e32 v18, 4, v18
	v_add_u32_e32 v3, 0, v3
	v_mul_u32_u24_e32 v44, 0x188, v140
	v_writelane_b32 v254, s77, 60
	v_lshl_add_u64 v[138:139], v[4:5], 0, s[62:63]
	s_movk_i32 s62, 0x6c00
	v_cmp_lt_i32_e64 s[6:7], -1, v10
	v_cmp_lt_i32_e64 s[8:9], -1, v14
	v_writelane_b32 v254, s3, 61
	s_mov_b64 s[76:77], 0
	v_add_u32_e32 v142, v27, v31
	v_add_u32_e32 v143, v27, v32
	v_add_u32_e32 v144, v27, v30
	v_add3_u32 v145, v19, v18, s62
	v_add3_u32 v146, v33, v34, s62
	v_add3_u32 v147, v3, v35, s62
	v_add_u32_e32 v148, v29, v36
	v_add_u32_e32 v149, v29, v37
	v_add_u32_e32 v150, v29, v38
	v_add_u32_e32 v151, v29, v39
	v_add_u32_e32 v152, v29, v40
	v_mbcnt_hi_u32_b32 v1, -1, v1
	v_add_u32_e32 v153, v43, v44
	v_add_u32_e32 v154, v41, v44
	v_add_u32_e32 v155, v42, v44
	v_add_u32_e32 v156, v45, v44
	v_add_u32_e32 v157, v46, v44
	s_mov_b64 s[78:79], 0x200000
	s_mov_b64 s[90:91], 0x80
	v_mov_b32_e32 v158, 0xff800000
	v_mov_b32_e32 v159, 0
	s_mov_b32 s3, 0x3fb8aa3b
	s_mov_b64 exec, s[0:1]
	v_lshl_add_u64 v[240:241], s[94:95], 0, v[130:131]
	global_load_dwordx4 v[200:203], v[240:241], off
	s_mov_b64 exec, s[6:7]
	v_lshl_add_u64 v[240:241], s[94:95], 0, v[132:133]
	global_load_dwordx4 v[204:207], v[240:241], off
	s_mov_b64 exec, s[8:9]
	v_lshl_add_u64 v[240:241], s[94:95], 0, v[134:135]
	global_load_dwordx4 v[208:211], v[240:241], off
	s_mov_b64 exec, s[10:11]
	v_lshl_add_u64 v[240:241], s[94:95], 0, v[124:125]
	global_load_dwordx4 v[212:215], v[240:241], off
	s_mov_b64 exec, s[12:13]
	v_lshl_add_u64 v[240:241], s[94:95], 0, v[126:127]
	global_load_dwordx4 v[216:219], v[240:241], off
	s_mov_b64 exec, s[14:15]
	v_lshl_add_u64 v[240:241], s[94:95], 0, v[128:129]
	global_load_dwordx4 v[220:223], v[240:241], off
	s_mov_b64 exec, -1
	v_lshl_add_u64 v[240:241], s[94:95], 0, v[138:139]
	global_load_dwordx4 v[224:227], v[240:241], off offset:-32
	global_load_dwordx4 v[228:231], v[240:241], off offset:-16
	global_load_dwordx4 v[232:235], v[240:241], off
	global_load_dwordx4 v[236:239], v[240:241], off offset:16
	s_add_u32 vcc_lo, s4, s76
	s_addc_u32 vcc_hi, s5, s77
	global_load_dword v242, v2, vcc
	s_branch .LBB0_656

; #define LAS __attribute__((address_space(3)))
; __device__ __forceinline__ void attn_phase(LAS unsigned char* lds, int vcu, int G, const bf16* Qp, const bf16* Kp, const bf16* Vt, const float* sinks, bf16* AO, int ldo, float* st) {
;     ...
;         const bf16* qrow = Qp + (tok0 + q0 + 32 * qsub + r32) * D_ATTN + h * HD + 32 * hi;
;         bf16x8 qf[4];
; #pragma unroll
;         for (int kk = 0; kk < 4; ++kk) qf[kk] = *(const bf16x8*)(qrow + 8 * kk);
; #pragma unroll
;         for (int i = 0; i < 3; ++i) { const int c = tid + 512 * i, row = c >> 3, ch = c & 7, key = q0 - 128 + row;
;             if (key >= 0) *(LAS v4u*)(lds + row * AT_KROW + ch * 16) = kv[i]; }
;     ...
;         const float sk = sinks[h] * 1.4426950408889634f;
.LBB0_656:
	s_waitcnt vmcnt(0)
	v_mov_b32_e32 v120, v224
	v_mov_b32_e32 v121, v225
	v_mov_b32_e32 v122, v226
	v_mov_b32_e32 v123, v227
	v_mov_b32_e32 v116, v228
	v_mov_b32_e32 v117, v229
	v_mov_b32_e32 v118, v230
	v_mov_b32_e32 v119, v231
	v_mov_b32_e32 v112, v232
	v_mov_b32_e32 v113, v233
	v_mov_b32_e32 v114, v234
	v_mov_b32_e32 v115, v235
	v_mov_b32_e32 v108, v236
	v_mov_b32_e32 v109, v237
	v_mov_b32_e32 v110, v238
	v_mov_b32_e32 v111, v239
	v_mov_b32_e32 v183, v242
	s_and_saveexec_b64 s[62:63], s[16:17]
	s_cbranch_execnz .LBB0_687
	s_or_b64 exec, exec, s[62:63]
	s_and_saveexec_b64 s[62:63], s[18:19]
	s_cbranch_execnz .LBB0_688

; __device__ __forceinline__ void attn_phase(LAS unsigned char* lds, int vcu, int G, const bf16* Qp, const bf16* Kp, const bf16* Vt, const float* sinks, bf16* AO, int ldo, float* st) {
;     ...
;         for (int i = 0; i < 3; ++i) { const int c = tid + 512 * i, row = c >> 3, ch = c & 7, key = q0 - 128 + row;
;             if (key >= 0) kv[i] = *(const v4u*)(Kp + (tok0 + key) * D_KV + kvh * HD + ch * 8); }
; #pragma unroll
;         for (int i = 0; i < 3; ++i) { const int c = tid + 512 * i, d = c / 24, ch = c - d * 24, key0 = q0 - 128 + 8 * ch;
;             if (key0 >= 0) vv[i] = *(const v4u*)(Vt + (size_t)(kvh * HD + d) * M + tok0 + key0); }
;         const bf16* qrow = Qp + (tok0 + q0 + 32 * qsub + r32) * D_ATTN + h * HD + 32 * hi;
;         bf16x8 qf[4];
; #pragma unroll
;         for (int kk = 0; kk < 4; ++kk) qf[kk] = *(const bf16x8*)(qrow + 8 * kk);
;     ...
;         const float sk = sinks[h] * 1.4426950408889634f;
.LBB0_680:
	s_nop 8
	v_cndmask_b32_e64 v185, v70, v158, s[34:35]
	v_and_b32_e32 v70, 64, v1
	v_cndmask_b32_e64 v184, v158, v69, s[30:31]
	v_xor_b32_e32 v69, 32, v1
	v_add_u32_e32 v173, 64, v70
	v_cndmask_b32_e64 v3, v68, v158, s[28:29]
	v_cmp_lt_i32_e32 vcc, v69, v173
	v_cndmask_b32_e64 v198, v3, v68, s[30:31]
	v_cndmask_b32_e64 v52, v158, v52, s[28:29]
	v_cndmask_b32_e32 v3, v1, v69, vcc
	v_cndmask_b32_e64 v53, v53, v158, s[30:31]
	v_lshlrev_b32_e32 v172, 2, v3
	v_cndmask_b32_e64 v54, v158, v54, s[34:35]
	v_cndmask_b32_e64 v55, v158, v55, s[36:37]
	v_cndmask_b32_e64 v56, v158, v56, s[38:39]
	v_cndmask_b32_e64 v57, v158, v57, s[40:41]
	v_cndmask_b32_e64 v58, v158, v58, s[42:43]
	v_cndmask_b32_e64 v59, v158, v59, s[44:45]
	v_cndmask_b32_e64 v60, v158, v60, s[46:47]
	v_cndmask_b32_e64 v61, v158, v61, s[48:49]
	v_cndmask_b32_e64 v62, v158, v62, s[50:51]
	v_cndmask_b32_e64 v63, v158, v63, s[52:53]
	v_cndmask_b32_e64 v64, v158, v64, s[54:55]
	v_cndmask_b32_e64 v65, v158, v65, s[56:57]
	v_cndmask_b32_e64 v66, v158, v66, s[58:59]
	v_cndmask_b32_e64 v67, v158, v67, s[60:61]
	v_cndmask_b32_e64 v186, v71, v158, s[36:37]
	v_cndmask_b32_e64 v187, v72, v158, s[38:39]
	v_cndmask_b32_e64 v188, v73, v158, s[40:41]
	v_cndmask_b32_e64 v189, v74, v158, s[42:43]
	v_cndmask_b32_e64 v190, v75, v158, s[44:45]
	v_cndmask_b32_e64 v191, v76, v158, s[46:47]
	v_cndmask_b32_e64 v192, v77, v158, s[48:49]
	v_cndmask_b32_e64 v193, v78, v158, s[50:51]
	v_cndmask_b32_e64 v194, v79, v158, s[52:53]
	v_cndmask_b32_e64 v195, v80, v158, s[54:55]
	v_cndmask_b32_e64 v81, v81, v158, s[56:57]
	v_cndmask_b32_e64 v196, v82, v158, s[58:59]
	v_cndmask_b32_e64 v197, v83, v158, s[60:61]
	s_waitcnt vmcnt(0)
	s_cmp_eq_u32 s76, 48
	s_cbranch_scc1 .Lattn_pf_skip
	v_lshl_add_u64 v[124:125], v[124:125], 0, s[78:79]
	v_lshl_add_u64 v[126:127], v[126:127], 0, s[78:79]
	v_lshl_add_u64 v[128:129], v[128:129], 0, s[78:79]
	v_lshl_add_u64 v[130:131], v[130:131], 0, s[90:91]
	v_lshl_add_u64 v[132:133], v[132:133], 0, s[90:91]
	v_lshl_add_u64 v[134:135], v[134:135], 0, s[90:91]
	v_lshl_add_u64 v[138:139], v[138:139], 0, s[86:87]
	s_mov_b64 exec, s[0:1]
	v_lshl_add_u64 v[240:241], s[94:95], 0, v[130:131]
	global_load_dwordx4 v[200:203], v[240:241], off
	s_mov_b64 exec, s[6:7]
	v_lshl_add_u64 v[240:241], s[94:95], 0, v[132:133]
	global_load_dwordx4 v[204:207], v[240:241], off
	s_mov_b64 exec, s[8:9]
	v_lshl_add_u64 v[240:241], s[94:95], 0, v[134:135]
	global_load_dwordx4 v[208:211], v[240:241], off
	s_mov_b64 exec, s[10:11]
	v_lshl_add_u64 v[240:241], s[94:95], 0, v[124:125]
	global_load_dwordx4 v[212:215], v[240:241], off
	s_mov_b64 exec, s[12:13]
	v_lshl_add_u64 v[240:241], s[94:95], 0, v[126:127]
	global_load_dwordx4 v[216:219], v[240:241], off
	s_mov_b64 exec, s[14:15]
	v_lshl_add_u64 v[240:241], s[94:95], 0, v[128:129]
	global_load_dwordx4 v[220:223], v[240:241], off
	s_mov_b64 exec, -1
	v_lshl_add_u64 v[240:241], s[94:95], 0, v[138:139]
	global_load_dwordx4 v[224:227], v[240:241], off offset:-32
	global_load_dwordx4 v[228:231], v[240:241], off offset:-16
	global_load_dwordx4 v[232:235], v[240:241], off
	global_load_dwordx4 v[236:239], v[240:241], off offset:16
	s_add_u32 vcc_lo, s4, s76
	s_addc_u32 vcc_hi, s5, s77
	s_add_u32 vcc_lo, vcc_lo, 16
	s_addc_u32 vcc_hi, vcc_hi, 0
	global_load_dword v242, v2, vcc
